# grid barrier: followers poll the global generation word directly instead of the per-XCD relay (one cross-chip hop less), plus previous combined changes
# baseline (speedup 1.0000x reference)
.LBB0_313:
	s_or_b64 exec, exec, s[2:3]
	v_cvt_f32_u32_e32 v5, v2
	s_waitcnt vmcnt(0)
	v_readfirstlane_b32 s2, v4
	v_sub_u32_e32 v4, 0, v2
	v_rcp_iflag_f32_e32 v5, v5
	v_add_u32_e32 v6, s2, v1
	v_mul_f32_e32 v5, 0x4f7ffffe, v5
	v_cvt_u32_f32_e32 v5, v5
	v_mul_lo_u32 v1, v4, v5
	v_mul_hi_u32 v1, v5, v1
	v_add_u32_e32 v1, v5, v1
	v_mul_hi_u32 v1, v6, v1
	v_mul_lo_u32 v4, v1, v2
	v_sub_u32_e32 v4, v6, v4
	v_add_u32_e32 v5, 1, v1
	v_cmp_ge_u32_e32 vcc, v4, v2
	s_nop 1
	v_cndmask_b32_e32 v1, v1, v5, vcc
	v_sub_u32_e32 v5, v4, v2
	v_cndmask_b32_e32 v4, v4, v5, vcc
	v_add_u32_e32 v5, 1, v1
	v_cmp_ge_u32_e32 vcc, v4, v2
	v_add_u32_e32 v4, 1, v6
	s_nop 0
	v_cndmask_b32_e32 v1, v1, v5, vcc
	v_mul_lo_u32 v5, v2, v1
	v_add_u32_e32 v2, v5, v2
	v_cmp_ne_u32_e32 vcc, v4, v2
	s_and_saveexec_b64 s[2:3], vcc
	s_xor_b64 s[2:3], exec, s[2:3]
	s_cbranch_execz .LBB0_327
	v_readlane_b32 s4, v252, 20
	v_readlane_b32 s5, v252, 21
	s_waitcnt lgkmcnt(0)
	s_nop 3
	global_load_dword v0, v3, s[4:5] sc1
	s_waitcnt vmcnt(0)
	v_cmp_eq_u32_e32 vcc, v0, v1
	s_and_saveexec_b64 s[4:5], vcc
	s_cbranch_execz .LBB0_326
	s_mov_b32 s18, 1
	s_mov_b64 s[6:7], 0
	s_branch .LBB0_317

.LBB0_319:
	v_readlane_b32 s16, v252, 20
	v_readlane_b32 s17, v252, 21
	s_add_i32 s18, s18, 1
	s_mov_b64 s[20:21], -1
	s_nop 2
	global_load_dword v0, v3, s[16:17] sc1
	s_waitcnt vmcnt(0)
	v_cmp_ne_u32_e32 vcc, v0, v1
	s_orn2_b64 s[16:17], vcc, exec
	s_branch .LBB0_316

.LBB0_582:
	s_or_b64 exec, exec, s[2:3]
	v_cvt_f32_u32_e32 v5, v2
	s_waitcnt vmcnt(0)
	v_readfirstlane_b32 s2, v4
	v_sub_u32_e32 v4, 0, v2
	v_rcp_iflag_f32_e32 v5, v5
	v_add_u32_e32 v6, s2, v1
	v_mul_f32_e32 v5, 0x4f7ffffe, v5
	v_cvt_u32_f32_e32 v5, v5
	v_mul_lo_u32 v1, v4, v5
	v_mul_hi_u32 v1, v5, v1
	v_add_u32_e32 v1, v5, v1
	v_mul_hi_u32 v1, v6, v1
	v_mul_lo_u32 v4, v1, v2
	v_sub_u32_e32 v4, v6, v4
	v_add_u32_e32 v5, 1, v1
	v_cmp_ge_u32_e32 vcc, v4, v2
	s_nop 1
	v_cndmask_b32_e32 v1, v1, v5, vcc
	v_sub_u32_e32 v5, v4, v2
	v_cndmask_b32_e32 v4, v4, v5, vcc
	v_add_u32_e32 v5, 1, v1
	v_cmp_ge_u32_e32 vcc, v4, v2
	v_add_u32_e32 v4, 1, v6
	s_nop 0
	v_cndmask_b32_e32 v1, v1, v5, vcc
	v_mul_lo_u32 v5, v2, v1
	v_add_u32_e32 v2, v5, v2
	v_cmp_ne_u32_e32 vcc, v4, v2
	s_and_saveexec_b64 s[2:3], vcc
	s_xor_b64 s[2:3], exec, s[2:3]
	s_cbranch_execz .LBB0_596
	v_readlane_b32 s4, v252, 20
	v_readlane_b32 s5, v252, 21
	s_waitcnt lgkmcnt(0)
	s_nop 3
	global_load_dword v0, v3, s[4:5] sc1
	s_waitcnt vmcnt(0)
	v_cmp_eq_u32_e32 vcc, v0, v1
	s_and_saveexec_b64 s[4:5], vcc
	s_cbranch_execz .LBB0_595
	s_mov_b32 s18, 1
	s_mov_b64 s[8:9], 0
	s_branch .LBB0_586

.LBB0_588:
	v_readlane_b32 s20, v252, 20
	v_readlane_b32 s21, v252, 21
	s_add_i32 s18, s18, 1
	s_mov_b64 s[22:23], -1
	s_nop 2
	global_load_dword v0, v3, s[20:21] sc1
	s_waitcnt vmcnt(0)
	v_cmp_ne_u32_e32 vcc, v0, v1
	s_orn2_b64 s[20:21], vcc, exec
	s_branch .LBB0_585

.LBB0_1051:
	s_or_b64 exec, exec, s[4:5]
	v_cvt_f32_u32_e32 v5, v2
	s_waitcnt vmcnt(0)
	v_readfirstlane_b32 s4, v4
	v_sub_u32_e32 v4, 0, v2
	v_rcp_iflag_f32_e32 v5, v5
	v_add_u32_e32 v6, s4, v1
	v_mul_f32_e32 v5, 0x4f7ffffe, v5
	v_cvt_u32_f32_e32 v5, v5
	v_mul_lo_u32 v1, v4, v5
	v_mul_hi_u32 v1, v5, v1
	v_add_u32_e32 v1, v5, v1
	v_mul_hi_u32 v1, v6, v1
	v_mul_lo_u32 v4, v1, v2
	v_sub_u32_e32 v4, v6, v4
	v_add_u32_e32 v5, 1, v1
	v_cmp_ge_u32_e32 vcc, v4, v2
	s_nop 1
	v_cndmask_b32_e32 v1, v1, v5, vcc
	v_sub_u32_e32 v5, v4, v2
	v_cndmask_b32_e32 v4, v4, v5, vcc
	v_add_u32_e32 v5, 1, v1
	v_cmp_ge_u32_e32 vcc, v4, v2
	v_add_u32_e32 v4, 1, v6
	s_nop 0
	v_cndmask_b32_e32 v1, v1, v5, vcc
	v_mul_lo_u32 v5, v2, v1
	v_add_u32_e32 v2, v5, v2
	v_cmp_ne_u32_e32 vcc, v4, v2
	s_and_saveexec_b64 s[4:5], vcc
	s_xor_b64 s[4:5], exec, s[4:5]
	s_cbranch_execz .LBB0_1065
	v_readlane_b32 s8, v252, 20
	v_readlane_b32 s9, v252, 21
	s_waitcnt lgkmcnt(0)
	s_nop 3
	global_load_dword v0, v3, s[8:9] sc1
	s_waitcnt vmcnt(0)
	v_cmp_eq_u32_e32 vcc, v0, v1
	s_and_saveexec_b64 s[8:9], vcc
	s_cbranch_execz .LBB0_1064
	s_mov_b32 s30, 1
	s_mov_b64 s[10:11], 0
	s_branch .LBB0_1055

.LBB0_1057:
	v_readlane_b32 s20, v252, 20
	v_readlane_b32 s21, v252, 21
	s_add_i32 s30, s30, 1
	s_mov_b64 s[22:23], -1
	s_nop 2
	global_load_dword v0, v3, s[20:21] sc1
	s_waitcnt vmcnt(0)
	v_cmp_ne_u32_e32 vcc, v0, v1
	s_orn2_b64 s[20:21], vcc, exec
	s_branch .LBB0_1054

.LBB0_1549:
	v_readlane_b32 s10, v252, 20
	v_readlane_b32 s11, v252, 21
	s_add_i32 s18, s18, 1
	s_mov_b64 s[16:17], -1
	s_nop 2
	global_load_dword v0, v3, s[10:11] sc1
	s_waitcnt vmcnt(0)
	v_cmp_ne_u32_e32 vcc, v0, v1
	s_orn2_b64 s[10:11], vcc, exec
	s_branch .LBB0_1546
